# GEMM k-step: second operand load set issued mid first half (all 8 LDS stores of the half already out), half a k-step more time to land
# baseline (speedup 1.0000x reference)
.Lg1w_w1:
	ds_write_b128 v141, v[68:71] offset:32768
	ds_write_b128 v141, v[76:79] offset:49152
	ds_write_b128 v141, v[84:87] offset:36864
	ds_write_b128 v141, v[92:95] offset:53248
	v_add_u32_e32 v153, v148, v143
	s_waitcnt lgkmcnt(4)
	v_mfma_f32_32x32x16_bf16 v[16:31], v[162:165], v[158:161], v[16:31]
	s_cmp_gt_u32 s39, 12
	v_mfma_f32_32x32x16_bf16 v[48:63], v[154:157], v[158:161], v[48:63]
	v_mfma_f32_32x32x16_bf16 v[32:47], v[154:157], v[166:169], v[32:47]
	ds_read_b128 v[156:159], v153
	v_add_u32_e32 v154, v148, v145
	v_add_u32_e32 v155, v149, v143
	v_mfma_f32_32x32x16_bf16 v[0:15], v[162:165], v[166:169], v[0:15]
	ds_read_b128 v[160:163], v154 offset:16384
	ds_read_b128 v[164:167], v153 offset:4096
	ds_read_b128 v[168:171], v154 offset:20480
	ds_write_b128 v141, v[100:103] offset:40960
	ds_write_b128 v141, v[108:111] offset:57344
	ds_write_b128 v141, v[116:119] offset:45056
	ds_write_b128 v141, v[124:127] offset:61440
	s_waitcnt lgkmcnt(4)
	v_mfma_f32_32x32x16_bf16 v[48:63], v[156:159], v[160:163], v[48:63]
	v_mfma_f32_32x32x16_bf16 v[32:47], v[156:159], v[168:171], v[32:47]
	v_add_u32_e32 v156, v149, v145
	v_add_u32_e32 v157, v150, v143
	v_mfma_f32_32x32x16_bf16 v[16:31], v[164:167], v[160:163], v[16:31]
	ds_read_b128 v[158:161], v155
	v_mfma_f32_32x32x16_bf16 v[0:15], v[164:167], v[168:171], v[0:15]
	ds_read_b128 v[162:165], v156 offset:16384
	ds_read_b128 v[166:169], v155 offset:4096
	ds_read_b128 v[170:173], v156 offset:20480
	s_cbranch_scc1 .Lg1w_nold
	v_add_co_u32_e32 v84, vcc, 0x10000, v136
	global_load_dwordx4 v[68:71], v[136:137], off offset:384
	global_load_dwordx4 v[76:79], v[134:135], off offset:384
	v_addc_co_u32_e32 v85, vcc, 0, v137, vcc
	v_add_co_u32_e32 v92, vcc, 0x10000, v134
	global_load_dwordx4 v[84:87], v[84:85], off offset:384
	s_nop 0
	v_addc_co_u32_e32 v93, vcc, 0, v135, vcc
	v_add_co_u32_e32 v100, vcc, 0x20000, v136
	global_load_dwordx4 v[92:95], v[92:93], off offset:384
	s_nop 0
	v_addc_co_u32_e32 v101, vcc, 0, v137, vcc
	v_add_co_u32_e32 v108, vcc, 0x20000, v134
	global_load_dwordx4 v[100:103], v[100:101], off offset:384
	s_nop 0
	v_addc_co_u32_e32 v109, vcc, 0, v135, vcc
	v_add_co_u32_e32 v116, vcc, 0x30000, v136
	global_load_dwordx4 v[108:111], v[108:109], off offset:384
	s_nop 0
	v_addc_co_u32_e32 v117, vcc, 0, v137, vcc
	v_add_co_u32_e32 v124, vcc, 0x30000, v134
	global_load_dwordx4 v[116:119], v[116:117], off offset:384
	s_nop 0
	v_addc_co_u32_e32 v125, vcc, 0, v135, vcc
	global_load_dwordx4 v[124:127], v[124:125], off offset:384
.Lg1w_nold:
	s_waitcnt lgkmcnt(0)
	v_mfma_f32_32x32x16_bf16 v[48:63], v[158:161], v[162:165], v[48:63]
	v_mfma_f32_32x32x16_bf16 v[32:47], v[158:161], v[170:173], v[32:47]
	v_add_u32_e32 v158, v150, v145
	v_mfma_f32_32x32x16_bf16 v[16:31], v[166:169], v[162:165], v[16:31]
	ds_read_b128 v[160:163], v157
	v_mfma_f32_32x32x16_bf16 v[0:15], v[166:169], v[170:173], v[0:15]
	ds_read_b128 v[164:167], v158 offset:16384
	ds_read_b128 v[168:171], v157 offset:4096
	ds_read_b128 v[172:175], v158 offset:20480
	s_waitcnt lgkmcnt(0)
	v_mfma_f32_32x32x16_bf16 v[48:63], v[160:163], v[164:167], v[48:63]
	v_mfma_f32_32x32x16_bf16 v[32:47], v[160:163], v[172:175], v[32:47]
	v_mfma_f32_32x32x16_bf16 v[16:31], v[168:171], v[164:167], v[16:31]
	v_mfma_f32_32x32x16_bf16 v[0:15], v[168:171], v[172:175], v[0:15]
	s_waitcnt lgkmcnt(0)
	s_barrier
	ds_read_b128 v[160:163], v152 offset:49152
	ds_read_b128 v[164:167], v151 offset:36864
	ds_read_b128 v[168:171], v152 offset:53248
	s_cbranch_scc1 .LBB0_888

.Lkqw_w1:
	ds_write_b128 v135, v[68:71] offset:32768
	ds_write_b128 v135, v[76:79] offset:49152
	ds_write_b128 v135, v[84:87] offset:36864
	ds_write_b128 v135, v[92:95] offset:53248
	v_add_u32_e32 v157, v143, v139
	s_waitcnt lgkmcnt(4)
	v_mfma_f32_32x32x16_bf16 v[0:15], v[226:229], v[222:225], v[0:15]
	v_add_u32_e32 v159, v143, v141
	v_add_u32_e32 v161, v149, v139
	v_add_u32_e32 v163, v149, v141
	v_add_u32_e32 v165, v151, v139
	v_add_u32_e32 v167, v151, v141
	s_cmp_gt_u32 s68, 12
	v_mfma_f32_32x32x16_bf16 v[32:47], v[218:221], v[222:225], v[32:47]
	v_mfma_f32_32x32x16_bf16 v[48:63], v[218:221], v[230:233], v[48:63]
	ds_read_b128 v[218:221], v157
	v_mfma_f32_32x32x16_bf16 v[16:31], v[226:229], v[230:233], v[16:31]
	ds_read_b128 v[222:225], v159 offset:16384
	ds_read_b128 v[226:229], v157 offset:4096
	ds_read_b128 v[230:233], v159 offset:20480
	ds_write_b128 v135, v[100:103] offset:40960
	ds_write_b128 v135, v[108:111] offset:57344
	ds_write_b128 v135, v[116:119] offset:45056
	ds_write_b128 v135, v[124:127] offset:61440
	s_waitcnt lgkmcnt(4)
	v_mfma_f32_32x32x16_bf16 v[32:47], v[218:221], v[222:225], v[32:47]
	v_mfma_f32_32x32x16_bf16 v[48:63], v[218:221], v[230:233], v[48:63]
	ds_read_b128 v[218:221], v161
	v_mfma_f32_32x32x16_bf16 v[0:15], v[226:229], v[222:225], v[0:15]
	v_mfma_f32_32x32x16_bf16 v[16:31], v[226:229], v[230:233], v[16:31]
	ds_read_b128 v[222:225], v163 offset:16384
	ds_read_b128 v[226:229], v161 offset:4096
	ds_read_b128 v[230:233], v163 offset:20480
	s_cbranch_scc1 .Lkqw_nold
	v_add_co_u32_e32 v84, vcc, 0x10000, v194
	global_load_dwordx4 v[68:71], v[194:195], off offset:384
	global_load_dwordx4 v[76:79], v[192:193], off offset:384
	v_addc_co_u32_e32 v85, vcc, 0, v195, vcc
	v_add_co_u32_e32 v92, vcc, 0x10000, v192
	global_load_dwordx4 v[84:87], v[84:85], off offset:384
	s_nop 0
	v_addc_co_u32_e32 v93, vcc, 0, v193, vcc
	v_add_co_u32_e32 v100, vcc, 0x20000, v194
	global_load_dwordx4 v[92:95], v[92:93], off offset:384
	s_nop 0
	v_addc_co_u32_e32 v101, vcc, 0, v195, vcc
	v_add_co_u32_e32 v108, vcc, 0x20000, v192
	global_load_dwordx4 v[100:103], v[100:101], off offset:384
	s_nop 0
	v_addc_co_u32_e32 v109, vcc, 0, v193, vcc
	v_add_co_u32_e32 v116, vcc, 0x30000, v194
	global_load_dwordx4 v[108:111], v[108:109], off offset:384
	s_nop 0
	v_addc_co_u32_e32 v117, vcc, 0, v195, vcc
	v_add_co_u32_e32 v124, vcc, 0x30000, v192
	global_load_dwordx4 v[116:119], v[116:117], off offset:384
	s_nop 0
	v_addc_co_u32_e32 v125, vcc, 0, v193, vcc
	global_load_dwordx4 v[124:127], v[124:125], off offset:384
.Lkqw_nold:
	s_waitcnt lgkmcnt(0)
	v_mfma_f32_32x32x16_bf16 v[32:47], v[218:221], v[222:225], v[32:47]
	v_mfma_f32_32x32x16_bf16 v[48:63], v[218:221], v[230:233], v[48:63]
	ds_read_b128 v[218:221], v165
	v_mfma_f32_32x32x16_bf16 v[0:15], v[226:229], v[222:225], v[0:15]
	v_mfma_f32_32x32x16_bf16 v[16:31], v[226:229], v[230:233], v[16:31]
	ds_read_b128 v[222:225], v167 offset:16384
	ds_read_b128 v[226:229], v165 offset:4096
	ds_read_b128 v[230:233], v167 offset:20480
	s_waitcnt lgkmcnt(0)
	v_mfma_f32_32x32x16_bf16 v[32:47], v[218:221], v[222:225], v[32:47]
	v_mfma_f32_32x32x16_bf16 v[48:63], v[218:221], v[230:233], v[48:63]
	v_mfma_f32_32x32x16_bf16 v[0:15], v[226:229], v[222:225], v[0:15]
	v_mfma_f32_32x32x16_bf16 v[16:31], v[226:229], v[230:233], v[16:31]
	s_waitcnt lgkmcnt(0)
	s_barrier
	ds_read_b128 v[218:221], v155 offset:49152
	ds_read_b128 v[222:225], v153 offset:36864
	ds_read_b128 v[226:229], v155 offset:53248
	s_cbranch_scc1 .LBB0_1012

.Lg2w_w1:
	ds_write_b128 v138, v[68:71] offset:32768
	ds_write_b128 v138, v[76:79] offset:49152
	ds_write_b128 v138, v[84:87] offset:36864
	ds_write_b128 v138, v[92:95] offset:53248
	v_add_u32_e32 v147, v142, v140
	s_waitcnt lgkmcnt(4)
	v_mfma_f32_32x32x16_bf16 v[16:31], v[156:159], v[152:155], v[16:31]
	s_cmp_gt_u32 s16, 12
	v_mfma_f32_32x32x16_bf16 v[48:63], v[148:151], v[152:155], v[48:63]
	v_mfma_f32_32x32x16_bf16 v[32:47], v[148:151], v[160:163], v[32:47]
	ds_read_b128 v[150:153], v147
	v_add_u32_e32 v148, v142, v141
	v_add_u32_e32 v149, v143, v140
	v_mfma_f32_32x32x16_bf16 v[0:15], v[156:159], v[160:163], v[0:15]
	ds_read_b128 v[154:157], v148 offset:16384
	ds_read_b128 v[158:161], v147 offset:4096
	ds_read_b128 v[162:165], v148 offset:20480
	ds_write_b128 v138, v[100:103] offset:40960
	ds_write_b128 v138, v[108:111] offset:57344
	ds_write_b128 v138, v[116:119] offset:45056
	ds_write_b128 v138, v[124:127] offset:61440
	s_waitcnt lgkmcnt(4)
	v_mfma_f32_32x32x16_bf16 v[48:63], v[150:153], v[154:157], v[48:63]
	v_mfma_f32_32x32x16_bf16 v[32:47], v[150:153], v[162:165], v[32:47]
	v_add_u32_e32 v150, v143, v141
	v_add_u32_e32 v151, v144, v140
	v_mfma_f32_32x32x16_bf16 v[16:31], v[158:161], v[154:157], v[16:31]
	ds_read_b128 v[152:155], v149
	v_mfma_f32_32x32x16_bf16 v[0:15], v[158:161], v[162:165], v[0:15]
	ds_read_b128 v[156:159], v150 offset:16384
	ds_read_b128 v[160:163], v149 offset:4096
	ds_read_b128 v[170:173], v150 offset:20480
	s_cbranch_scc1 .Lg2w_nold
	v_add_co_u32_e32 v84, vcc, 0x10000, v136
	global_load_dwordx4 v[68:71], v[136:137], off offset:384
	global_load_dwordx4 v[76:79], v[134:135], off offset:384
	v_addc_co_u32_e32 v85, vcc, 0, v137, vcc
	v_add_co_u32_e32 v92, vcc, 0x10000, v134
	global_load_dwordx4 v[84:87], v[84:85], off offset:384
	s_nop 0
	v_addc_co_u32_e32 v93, vcc, 0, v135, vcc
	v_add_co_u32_e32 v100, vcc, 0x20000, v136
	global_load_dwordx4 v[92:95], v[92:93], off offset:384
	s_nop 0
	v_addc_co_u32_e32 v101, vcc, 0, v137, vcc
	v_add_co_u32_e32 v108, vcc, 0x20000, v134
	global_load_dwordx4 v[100:103], v[100:101], off offset:384
	s_nop 0
	v_addc_co_u32_e32 v109, vcc, 0, v135, vcc
	v_add_co_u32_e32 v116, vcc, 0x30000, v136
	global_load_dwordx4 v[108:111], v[108:109], off offset:384
	s_nop 0
	v_addc_co_u32_e32 v117, vcc, 0, v137, vcc
	v_add_co_u32_e32 v124, vcc, 0x30000, v134
	global_load_dwordx4 v[116:119], v[116:117], off offset:384
	s_nop 0
	v_addc_co_u32_e32 v125, vcc, 0, v135, vcc
	global_load_dwordx4 v[124:127], v[124:125], off offset:384
.Lg2w_nold:
	s_waitcnt lgkmcnt(0)
	v_mfma_f32_32x32x16_bf16 v[48:63], v[152:155], v[156:159], v[48:63]
	v_mfma_f32_32x32x16_bf16 v[32:47], v[152:155], v[170:173], v[32:47]
	v_add_u32_e32 v152, v144, v141
	v_mfma_f32_32x32x16_bf16 v[16:31], v[160:163], v[156:159], v[16:31]
	ds_read_b128 v[154:157], v151
	v_mfma_f32_32x32x16_bf16 v[0:15], v[160:163], v[170:173], v[0:15]
	ds_read_b128 v[158:161], v152 offset:16384
	ds_read_b128 v[162:165], v151 offset:4096
	ds_read_b128 v[170:173], v152 offset:20480
	s_waitcnt lgkmcnt(0)
	v_mfma_f32_32x32x16_bf16 v[48:63], v[154:157], v[158:161], v[48:63]
	v_mfma_f32_32x32x16_bf16 v[32:47], v[154:157], v[170:173], v[32:47]
	v_mfma_f32_32x32x16_bf16 v[16:31], v[162:165], v[158:161], v[16:31]
	v_mfma_f32_32x32x16_bf16 v[0:15], v[162:165], v[170:173], v[0:15]
	s_waitcnt lgkmcnt(0)
	s_barrier
	ds_read_b128 v[154:157], v146 offset:49152
	ds_read_b128 v[158:161], v145 offset:36864
	ds_read_b128 v[162:165], v146 offset:53248
	s_cbranch_scc1 .LBB0_1510
